# k29: k27 with the throw-away second-half residual touches issued as single-dword loads instead of dwordx4
# speedup vs baseline: 1.0112x; 1.0112x over previous
.LBB0_587:
	s_lshl_b32 s13, s13, 8
	v_lshl_or_b32 v170, s12, 8, v184
	v_add_u32_e32 v174, s13, v182
	v_ashrrev_i32_e32 v171, 31, v170
	v_lshlrev_b64 v[200:201], 1, v[170:171]
	v_ashrrev_i32_e32 v175, 31, v174
	v_lshl_add_u64 v[172:173], s[78:79], 0, v[200:201]
	v_lshlrev_b64 v[202:203], 11, v[174:175]
	v_lshl_add_u64 v[130:131], v[172:173], 0, v[202:203]
	global_load_dwordx4 v[192:195], v[130:131], off
	global_load_dwordx4 v[196:199], v[130:131], off offset:256
	v_or_b32_e32 v130, 16, v174
	v_or_b32_e32 v132, 32, v174
	v_or_b32_e32 v134, 48, v174
	v_ashrrev_i32_e32 v131, 31, v130
	v_ashrrev_i32_e32 v133, 31, v132
	v_ashrrev_i32_e32 v135, 31, v134
	v_lshlrev_b64 v[180:181], 11, v[130:131]
	v_lshlrev_b64 v[178:179], 11, v[132:133]
	v_lshlrev_b64 v[176:177], 11, v[134:135]
	v_lshl_add_u64 v[130:131], v[172:173], 0, v[180:181]
	v_lshl_add_u64 v[132:133], v[172:173], 0, v[178:179]
	v_lshl_add_u64 v[204:205], v[172:173], 0, v[176:177]
	v_add_co_u32_e32 v230, vcc, 0x38000, v130
	s_nop 1
	v_addc_co_u32_e32 v231, vcc, 0, v131, vcc
	v_add_co_u32_e32 v232, vcc, 0x40000, v130
	s_nop 1
	v_addc_co_u32_e32 v233, vcc, 0, v131, vcc
	v_add_co_u32_e32 v234, vcc, 0x40000, v132
	s_nop 1
	v_addc_co_u32_e32 v235, vcc, 0, v133, vcc
	v_add_co_u32_e32 v236, vcc, 0x40000, v204
	s_nop 1
	v_addc_co_u32_e32 v237, vcc, 0, v205, vcc
	global_load_dwordx4 v[150:153], v[130:131], off
	global_load_dwordx4 v[146:149], v[130:131], off offset:256
	global_load_dwordx4 v[142:145], v[132:133], off
	global_load_dwordx4 v[138:141], v[132:133], off offset:256
	global_load_dwordx4 v[134:137], v[204:205], off
	s_nop 0
	global_load_dwordx4 v[130:133], v[204:205], off offset:256
	global_load_dword v246, v[230:231], off
	global_load_dword v246, v[230:231], off offset:256
	global_load_dword v246, v[232:233], off
	global_load_dword v246, v[232:233], off offset:256
	global_load_dword v246, v[234:235], off
	global_load_dword v246, v[234:235], off offset:256
	global_load_dword v246, v[236:237], off
	global_load_dword v246, v[236:237], off offset:256
	v_and_b32_e32 v204, 64, v190
	v_xor_b32_e32 v191, 16, v190
	v_add_u32_e32 v204, 64, v204
	v_xor_b32_e32 v205, 32, v190
	v_cmp_lt_i32_e32 vcc, v191, v204
	v_lshl_add_u64 v[202:203], s[78:79], 0, v[202:203]
	v_lshl_add_u64 v[200:201], v[202:203], 0, v[200:201]
	v_cndmask_b32_e32 v191, v190, v191, vcc
	v_cmp_lt_i32_e32 vcc, v205, v204
	v_lshlrev_b32_e32 v191, 2, v191
	s_waitcnt vmcnt(8) lgkmcnt(15)
	v_lshlrev_b32_e32 v204, 16, v194
	v_cndmask_b32_e32 v210, v190, v205, vcc
	v_and_b32_e32 v205, 0xffff0000, v194
	v_lshlrev_b32_e32 v194, 16, v195
	v_and_b32_e32 v195, 0xffff0000, v195
	v_lshlrev_b32_e32 v202, 16, v192
	v_and_b32_e32 v203, 0xffff0000, v192
	v_lshlrev_b32_e32 v192, 16, v193
	v_and_b32_e32 v193, 0xffff0000, v193
	v_lshlrev_b32_e32 v206, 16, v196
	v_and_b32_e32 v207, 0xffff0000, v196
	v_lshlrev_b32_e32 v196, 16, v197
	v_and_b32_e32 v197, 0xffff0000, v197
	v_lshlrev_b32_e32 v208, 16, v198
	v_and_b32_e32 v209, 0xffff0000, v198
	v_lshlrev_b32_e32 v198, 16, v199
	v_and_b32_e32 v199, 0xffff0000, v199
	v_pk_add_f32 v[124:125], v[124:125], v[194:195]
	v_pk_add_f32 v[122:123], v[122:123], v[204:205]
	v_pk_add_f32 v[126:127], v[126:127], v[202:203]
	v_pk_add_f32 v[128:129], v[128:129], v[192:193]
	v_pk_add_f32 v[120:121], v[120:121], v[196:197]
	v_pk_add_f32 v[194:195], v[116:117], v[198:199]
	v_pk_mul_f32 v[116:117], v[122:123], v[122:123]
	v_pk_mul_f32 v[196:197], v[124:125], v[124:125]
	v_pk_add_f32 v[118:119], v[118:119], v[206:207]
	v_pk_add_f32 v[192:193], v[114:115], v[208:209]
	v_cvt_pk_bf16_f32 v114, v126, v127
	v_cvt_pk_bf16_f32 v115, v128, v129
	v_pk_fma_f32 v[128:129], v[128:129], v[128:129], v[196:197]
	v_pk_fma_f32 v[116:117], v[126:127], v[126:127], v[116:117]
	v_pk_fma_f32 v[126:127], v[120:121], v[120:121], v[128:129]
	v_pk_fma_f32 v[116:117], v[118:119], v[118:119], v[116:117]
	v_pk_fma_f32 v[126:127], v[194:195], v[194:195], v[126:127]
	v_pk_fma_f32 v[116:117], v[192:193], v[192:193], v[116:117]
	s_nop 0
	v_add_f32_e32 v116, v116, v117
	v_add_f32_e32 v117, v126, v127
	v_add_f32_e32 v126, v116, v117
	ds_bpermute_b32 v127, v191, v126
	v_cvt_pk_bf16_f32 v116, v122, v123
	v_cvt_pk_bf16_f32 v117, v124, v125
	global_store_dwordx4 v[200:201], v[114:117], off
	v_cvt_pk_bf16_f32 v118, v118, v119
	v_cvt_pk_bf16_f32 v119, v120, v121
	v_cvt_pk_bf16_f32 v120, v192, v193
	v_cvt_pk_bf16_f32 v121, v194, v195
	global_store_dwordx4 v[200:201], v[118:121], off offset:256
	s_waitcnt lgkmcnt(0)
	v_add_f32_e32 v115, v126, v127
	v_lshlrev_b32_e32 v114, 2, v210
	ds_bpermute_b32 v116, v114, v115
	s_and_saveexec_b64 s[2:3], s[4:5]
	s_cbranch_execz .LBB0_589
	s_waitcnt lgkmcnt(0)
	v_add_f32_e32 v115, v115, v116
	ds_write_b32 v185, v115

.LBB0_923:
	s_lshl_b32 s11, s26, 8
	v_lshl_or_b32 v170, s10, 8, v184
	v_add_u32_e32 v174, s11, v182
	v_ashrrev_i32_e32 v171, 31, v170
	v_lshlrev_b64 v[200:201], 1, v[170:171]
	v_ashrrev_i32_e32 v175, 31, v174
	v_lshl_add_u64 v[172:173], s[78:79], 0, v[200:201]
	v_lshlrev_b64 v[202:203], 11, v[174:175]
	v_lshl_add_u64 v[130:131], v[172:173], 0, v[202:203]
	global_load_dwordx4 v[192:195], v[130:131], off
	global_load_dwordx4 v[196:199], v[130:131], off offset:256
	v_or_b32_e32 v130, 16, v174
	v_or_b32_e32 v132, 32, v174
	v_or_b32_e32 v134, 48, v174
	v_ashrrev_i32_e32 v131, 31, v130
	v_ashrrev_i32_e32 v133, 31, v132
	v_ashrrev_i32_e32 v135, 31, v134
	v_lshlrev_b64 v[180:181], 11, v[130:131]
	v_lshlrev_b64 v[178:179], 11, v[132:133]
	v_lshlrev_b64 v[176:177], 11, v[134:135]
	v_lshl_add_u64 v[130:131], v[172:173], 0, v[180:181]
	v_lshl_add_u64 v[132:133], v[172:173], 0, v[178:179]
	v_lshl_add_u64 v[204:205], v[172:173], 0, v[176:177]
	v_add_co_u32_e32 v230, vcc, 0x38000, v130
	s_nop 1
	v_addc_co_u32_e32 v231, vcc, 0, v131, vcc
	v_add_co_u32_e32 v232, vcc, 0x40000, v130
	s_nop 1
	v_addc_co_u32_e32 v233, vcc, 0, v131, vcc
	v_add_co_u32_e32 v234, vcc, 0x40000, v132
	s_nop 1
	v_addc_co_u32_e32 v235, vcc, 0, v133, vcc
	v_add_co_u32_e32 v236, vcc, 0x40000, v204
	s_nop 1
	v_addc_co_u32_e32 v237, vcc, 0, v205, vcc
	global_load_dwordx4 v[150:153], v[130:131], off
	global_load_dwordx4 v[146:149], v[130:131], off offset:256
	global_load_dwordx4 v[142:145], v[132:133], off
	global_load_dwordx4 v[138:141], v[132:133], off offset:256
	global_load_dwordx4 v[134:137], v[204:205], off
	s_nop 0
	global_load_dwordx4 v[130:133], v[204:205], off offset:256
	global_load_dword v246, v[230:231], off
	global_load_dword v246, v[230:231], off offset:256
	global_load_dword v246, v[232:233], off
	global_load_dword v246, v[232:233], off offset:256
	global_load_dword v246, v[234:235], off
	global_load_dword v246, v[234:235], off offset:256
	global_load_dword v246, v[236:237], off
	global_load_dword v246, v[236:237], off offset:256
	v_and_b32_e32 v204, 64, v190
	v_xor_b32_e32 v191, 16, v190
	v_add_u32_e32 v204, 64, v204
	v_xor_b32_e32 v205, 32, v190
	v_cmp_lt_i32_e32 vcc, v191, v204
	v_lshl_add_u64 v[202:203], s[78:79], 0, v[202:203]
	v_lshl_add_u64 v[200:201], v[202:203], 0, v[200:201]
	v_cndmask_b32_e32 v191, v190, v191, vcc
	v_cmp_lt_i32_e32 vcc, v205, v204
	v_lshlrev_b32_e32 v191, 2, v191
	s_waitcnt vmcnt(8) lgkmcnt(15)
	v_lshlrev_b32_e32 v204, 16, v194
	v_cndmask_b32_e32 v210, v190, v205, vcc
	v_and_b32_e32 v205, 0xffff0000, v194
	v_lshlrev_b32_e32 v194, 16, v195
	v_and_b32_e32 v195, 0xffff0000, v195
	v_lshlrev_b32_e32 v202, 16, v192
	v_and_b32_e32 v203, 0xffff0000, v192
	v_lshlrev_b32_e32 v192, 16, v193
	v_and_b32_e32 v193, 0xffff0000, v193
	v_lshlrev_b32_e32 v206, 16, v196
	v_and_b32_e32 v207, 0xffff0000, v196
	v_lshlrev_b32_e32 v196, 16, v197
	v_and_b32_e32 v197, 0xffff0000, v197
	v_lshlrev_b32_e32 v208, 16, v198
	v_and_b32_e32 v209, 0xffff0000, v198
	v_lshlrev_b32_e32 v198, 16, v199
	v_and_b32_e32 v199, 0xffff0000, v199
	v_pk_add_f32 v[124:125], v[124:125], v[194:195]
	v_pk_add_f32 v[122:123], v[122:123], v[204:205]
	v_pk_add_f32 v[126:127], v[126:127], v[202:203]
	v_pk_add_f32 v[128:129], v[128:129], v[192:193]
	v_pk_add_f32 v[120:121], v[120:121], v[196:197]
	v_pk_add_f32 v[194:195], v[116:117], v[198:199]
	v_pk_mul_f32 v[116:117], v[122:123], v[122:123]
	v_pk_mul_f32 v[196:197], v[124:125], v[124:125]
	v_pk_add_f32 v[118:119], v[118:119], v[206:207]
	v_pk_add_f32 v[192:193], v[114:115], v[208:209]
	v_cvt_pk_bf16_f32 v114, v126, v127
	v_cvt_pk_bf16_f32 v115, v128, v129
	v_pk_fma_f32 v[128:129], v[128:129], v[128:129], v[196:197]
	v_pk_fma_f32 v[116:117], v[126:127], v[126:127], v[116:117]
	v_pk_fma_f32 v[126:127], v[120:121], v[120:121], v[128:129]
	v_pk_fma_f32 v[116:117], v[118:119], v[118:119], v[116:117]
	v_pk_fma_f32 v[126:127], v[194:195], v[194:195], v[126:127]
	v_pk_fma_f32 v[116:117], v[192:193], v[192:193], v[116:117]
	s_nop 0
	v_add_f32_e32 v116, v116, v117
	v_add_f32_e32 v117, v126, v127
	v_add_f32_e32 v126, v116, v117
	ds_bpermute_b32 v127, v191, v126
	v_cvt_pk_bf16_f32 v116, v122, v123
	v_cvt_pk_bf16_f32 v117, v124, v125
	global_store_dwordx4 v[200:201], v[114:117], off
	v_cvt_pk_bf16_f32 v118, v118, v119
	v_cvt_pk_bf16_f32 v119, v120, v121
	v_cvt_pk_bf16_f32 v120, v192, v193
	v_cvt_pk_bf16_f32 v121, v194, v195
	global_store_dwordx4 v[200:201], v[118:121], off offset:256
	s_waitcnt lgkmcnt(0)
	v_add_f32_e32 v115, v126, v127
	v_lshlrev_b32_e32 v114, 2, v210
	ds_bpermute_b32 v116, v114, v115
	s_and_saveexec_b64 s[2:3], s[4:5]
	s_cbranch_execz .LBB0_925
	s_waitcnt lgkmcnt(0)
	v_add_f32_e32 v115, v115, v116
	ds_write_b32 v185, v115

.LBB0_1629:
	s_lshl_b32 s11, s36, 8
	v_lshl_or_b32 v170, s10, 8, v183
	v_add_u32_e32 v174, s11, v1
	v_ashrrev_i32_e32 v171, 31, v170
	v_lshlrev_b64 v[200:201], 1, v[170:171]
	v_ashrrev_i32_e32 v175, 31, v174
	v_lshl_add_u64 v[172:173], s[78:79], 0, v[200:201]
	v_lshlrev_b64 v[202:203], 11, v[174:175]
	v_lshl_add_u64 v[130:131], v[172:173], 0, v[202:203]
	global_load_dwordx4 v[192:195], v[130:131], off
	global_load_dwordx4 v[196:199], v[130:131], off offset:256
	v_or_b32_e32 v130, 16, v174
	v_or_b32_e32 v132, 32, v174
	v_or_b32_e32 v134, 48, v174
	v_ashrrev_i32_e32 v131, 31, v130
	v_ashrrev_i32_e32 v133, 31, v132
	v_ashrrev_i32_e32 v135, 31, v134
	v_lshlrev_b64 v[180:181], 11, v[130:131]
	v_lshlrev_b64 v[178:179], 11, v[132:133]
	v_lshlrev_b64 v[176:177], 11, v[134:135]
	v_lshl_add_u64 v[130:131], v[172:173], 0, v[180:181]
	v_lshl_add_u64 v[132:133], v[172:173], 0, v[178:179]
	v_lshl_add_u64 v[190:191], v[172:173], 0, v[176:177]
	v_add_co_u32_e32 v230, vcc, 0x38000, v130
	s_nop 1
	v_addc_co_u32_e32 v231, vcc, 0, v131, vcc
	v_add_co_u32_e32 v232, vcc, 0x40000, v130
	s_nop 1
	v_addc_co_u32_e32 v233, vcc, 0, v131, vcc
	v_add_co_u32_e32 v234, vcc, 0x40000, v132
	s_nop 1
	v_addc_co_u32_e32 v235, vcc, 0, v133, vcc
	v_add_co_u32_e32 v236, vcc, 0x40000, v190
	s_nop 1
	v_addc_co_u32_e32 v237, vcc, 0, v191, vcc
	global_load_dwordx4 v[150:153], v[130:131], off
	global_load_dwordx4 v[146:149], v[130:131], off offset:256
	global_load_dwordx4 v[142:145], v[132:133], off
	global_load_dwordx4 v[138:141], v[132:133], off offset:256
	global_load_dwordx4 v[134:137], v[190:191], off
	s_nop 0
	global_load_dwordx4 v[130:133], v[190:191], off offset:256
	global_load_dword v246, v[230:231], off
	global_load_dword v246, v[230:231], off offset:256
	global_load_dword v246, v[232:233], off
	global_load_dword v246, v[232:233], off offset:256
	global_load_dword v246, v[234:235], off
	global_load_dword v246, v[234:235], off offset:256
	global_load_dword v246, v[236:237], off
	global_load_dword v246, v[236:237], off offset:256
	v_and_b32_e32 v191, 64, v189
	v_xor_b32_e32 v190, 16, v189
	v_add_u32_e32 v191, 64, v191
	v_xor_b32_e32 v204, 32, v189
	v_cmp_lt_i32_e32 vcc, v190, v191
	v_lshl_add_u64 v[202:203], s[78:79], 0, v[202:203]
	v_lshl_add_u64 v[200:201], v[202:203], 0, v[200:201]
	v_cndmask_b32_e32 v190, v189, v190, vcc
	v_cmp_lt_i32_e32 vcc, v204, v191
	v_lshlrev_b32_e32 v190, 2, v190
	s_waitcnt vmcnt(8) lgkmcnt(15)
	v_and_b32_e32 v205, 0xffff0000, v194
	v_cndmask_b32_e32 v191, v189, v204, vcc
	v_lshlrev_b32_e32 v204, 16, v194
	v_lshlrev_b32_e32 v194, 16, v195
	v_and_b32_e32 v195, 0xffff0000, v195
	v_lshlrev_b32_e32 v202, 16, v192
	v_and_b32_e32 v203, 0xffff0000, v192
	v_lshlrev_b32_e32 v192, 16, v193
	v_and_b32_e32 v193, 0xffff0000, v193
	v_lshlrev_b32_e32 v206, 16, v196
	v_and_b32_e32 v207, 0xffff0000, v196
	v_lshlrev_b32_e32 v196, 16, v197
	v_and_b32_e32 v197, 0xffff0000, v197
	v_lshlrev_b32_e32 v208, 16, v198
	v_and_b32_e32 v209, 0xffff0000, v198
	v_lshlrev_b32_e32 v198, 16, v199
	v_and_b32_e32 v199, 0xffff0000, v199
	v_pk_add_f32 v[124:125], v[124:125], v[194:195]
	v_pk_add_f32 v[122:123], v[122:123], v[204:205]
	v_pk_add_f32 v[126:127], v[126:127], v[202:203]
	v_pk_add_f32 v[128:129], v[128:129], v[192:193]
	v_pk_add_f32 v[120:121], v[120:121], v[196:197]
	v_pk_add_f32 v[194:195], v[116:117], v[198:199]
	v_pk_mul_f32 v[116:117], v[122:123], v[122:123]
	v_pk_mul_f32 v[196:197], v[124:125], v[124:125]
	v_pk_add_f32 v[118:119], v[118:119], v[206:207]
	v_pk_add_f32 v[192:193], v[114:115], v[208:209]
	v_cvt_pk_bf16_f32 v114, v126, v127
	v_cvt_pk_bf16_f32 v115, v128, v129
	v_pk_fma_f32 v[128:129], v[128:129], v[128:129], v[196:197]
	v_pk_fma_f32 v[116:117], v[126:127], v[126:127], v[116:117]
	v_pk_fma_f32 v[126:127], v[120:121], v[120:121], v[128:129]
	v_pk_fma_f32 v[116:117], v[118:119], v[118:119], v[116:117]
	v_pk_fma_f32 v[126:127], v[194:195], v[194:195], v[126:127]
	v_pk_fma_f32 v[116:117], v[192:193], v[192:193], v[116:117]
	s_nop 0
	v_add_f32_e32 v116, v116, v117
	v_add_f32_e32 v117, v126, v127
	v_add_f32_e32 v126, v116, v117
	ds_bpermute_b32 v127, v190, v126
	v_cvt_pk_bf16_f32 v116, v122, v123
	v_cvt_pk_bf16_f32 v117, v124, v125
	global_store_dwordx4 v[200:201], v[114:117], off
	v_cvt_pk_bf16_f32 v118, v118, v119
	v_cvt_pk_bf16_f32 v119, v120, v121
	v_cvt_pk_bf16_f32 v120, v192, v193
	v_cvt_pk_bf16_f32 v121, v194, v195
	global_store_dwordx4 v[200:201], v[118:121], off offset:256
	s_waitcnt lgkmcnt(0)
	v_add_f32_e32 v115, v126, v127
	v_lshlrev_b32_e32 v114, 2, v191
	ds_bpermute_b32 v116, v114, v115
	s_and_saveexec_b64 s[2:3], s[4:5]
	s_cbranch_execz .LBB0_1631
	s_waitcnt lgkmcnt(0)
	v_add_f32_e32 v115, v115, v116
	ds_write_b32 v184, v115

.LBB0_1844:
	s_lshl_b32 s13, s13, 8
	v_lshl_or_b32 v170, s12, 8, v183
	v_add_u32_e32 v174, s13, v1
	v_ashrrev_i32_e32 v171, 31, v170
	v_lshlrev_b64 v[200:201], 1, v[170:171]
	v_ashrrev_i32_e32 v175, 31, v174
	v_lshl_add_u64 v[172:173], s[78:79], 0, v[200:201]
	v_lshlrev_b64 v[202:203], 11, v[174:175]
	v_lshl_add_u64 v[130:131], v[172:173], 0, v[202:203]
	global_load_dwordx4 v[192:195], v[130:131], off
	global_load_dwordx4 v[196:199], v[130:131], off offset:256
	v_or_b32_e32 v130, 16, v174
	v_or_b32_e32 v132, 32, v174
	v_or_b32_e32 v134, 48, v174
	v_ashrrev_i32_e32 v131, 31, v130
	v_ashrrev_i32_e32 v133, 31, v132
	v_ashrrev_i32_e32 v135, 31, v134
	v_lshlrev_b64 v[180:181], 11, v[130:131]
	v_lshlrev_b64 v[178:179], 11, v[132:133]
	v_lshlrev_b64 v[176:177], 11, v[134:135]
	v_lshl_add_u64 v[130:131], v[172:173], 0, v[180:181]
	v_lshl_add_u64 v[132:133], v[172:173], 0, v[178:179]
	v_lshl_add_u64 v[190:191], v[172:173], 0, v[176:177]
	v_add_co_u32_e32 v230, vcc, 0x38000, v130
	s_nop 1
	v_addc_co_u32_e32 v231, vcc, 0, v131, vcc
	v_add_co_u32_e32 v232, vcc, 0x40000, v130
	s_nop 1
	v_addc_co_u32_e32 v233, vcc, 0, v131, vcc
	v_add_co_u32_e32 v234, vcc, 0x40000, v132
	s_nop 1
	v_addc_co_u32_e32 v235, vcc, 0, v133, vcc
	v_add_co_u32_e32 v236, vcc, 0x40000, v190
	s_nop 1
	v_addc_co_u32_e32 v237, vcc, 0, v191, vcc
	global_load_dwordx4 v[150:153], v[130:131], off
	global_load_dwordx4 v[146:149], v[130:131], off offset:256
	global_load_dwordx4 v[142:145], v[132:133], off
	global_load_dwordx4 v[138:141], v[132:133], off offset:256
	global_load_dwordx4 v[134:137], v[190:191], off
	s_nop 0
	global_load_dwordx4 v[130:133], v[190:191], off offset:256
	global_load_dword v246, v[230:231], off
	global_load_dword v246, v[230:231], off offset:256
	global_load_dword v246, v[232:233], off
	global_load_dword v246, v[232:233], off offset:256
	global_load_dword v246, v[234:235], off
	global_load_dword v246, v[234:235], off offset:256
	global_load_dword v246, v[236:237], off
	global_load_dword v246, v[236:237], off offset:256
	v_and_b32_e32 v191, 64, v189
	v_xor_b32_e32 v190, 16, v189
	v_add_u32_e32 v191, 64, v191
	v_xor_b32_e32 v204, 32, v189
	v_cmp_lt_i32_e32 vcc, v190, v191
	v_lshl_add_u64 v[202:203], s[78:79], 0, v[202:203]
	v_lshl_add_u64 v[200:201], v[202:203], 0, v[200:201]
	v_cndmask_b32_e32 v190, v189, v190, vcc
	v_cmp_lt_i32_e32 vcc, v204, v191
	v_lshlrev_b32_e32 v190, 2, v190
	s_waitcnt vmcnt(8) lgkmcnt(15)
	v_and_b32_e32 v205, 0xffff0000, v194
	v_cndmask_b32_e32 v191, v189, v204, vcc
	v_lshlrev_b32_e32 v204, 16, v194
	v_lshlrev_b32_e32 v194, 16, v195
	v_and_b32_e32 v195, 0xffff0000, v195
	v_lshlrev_b32_e32 v202, 16, v192
	v_and_b32_e32 v203, 0xffff0000, v192
	v_lshlrev_b32_e32 v192, 16, v193
	v_and_b32_e32 v193, 0xffff0000, v193
	v_lshlrev_b32_e32 v206, 16, v196
	v_and_b32_e32 v207, 0xffff0000, v196
	v_lshlrev_b32_e32 v196, 16, v197
	v_and_b32_e32 v197, 0xffff0000, v197
	v_lshlrev_b32_e32 v208, 16, v198
	v_and_b32_e32 v209, 0xffff0000, v198
	v_lshlrev_b32_e32 v198, 16, v199
	v_and_b32_e32 v199, 0xffff0000, v199
	v_pk_add_f32 v[124:125], v[124:125], v[194:195]
	v_pk_add_f32 v[122:123], v[122:123], v[204:205]
	v_pk_add_f32 v[126:127], v[126:127], v[202:203]
	v_pk_add_f32 v[128:129], v[128:129], v[192:193]
	v_pk_add_f32 v[120:121], v[120:121], v[196:197]
	v_pk_add_f32 v[194:195], v[116:117], v[198:199]
	v_pk_mul_f32 v[116:117], v[122:123], v[122:123]
	v_pk_mul_f32 v[196:197], v[124:125], v[124:125]
	v_pk_add_f32 v[118:119], v[118:119], v[206:207]
	v_pk_add_f32 v[192:193], v[114:115], v[208:209]
	v_cvt_pk_bf16_f32 v114, v126, v127
	v_cvt_pk_bf16_f32 v115, v128, v129
	v_pk_fma_f32 v[128:129], v[128:129], v[128:129], v[196:197]
	v_pk_fma_f32 v[116:117], v[126:127], v[126:127], v[116:117]
	v_pk_fma_f32 v[126:127], v[120:121], v[120:121], v[128:129]
	v_pk_fma_f32 v[116:117], v[118:119], v[118:119], v[116:117]
	v_pk_fma_f32 v[126:127], v[194:195], v[194:195], v[126:127]
	v_pk_fma_f32 v[116:117], v[192:193], v[192:193], v[116:117]
	s_nop 0
	v_add_f32_e32 v116, v116, v117
	v_add_f32_e32 v117, v126, v127
	v_add_f32_e32 v126, v116, v117
	ds_bpermute_b32 v127, v190, v126
	v_cvt_pk_bf16_f32 v116, v122, v123
	v_cvt_pk_bf16_f32 v117, v124, v125
	global_store_dwordx4 v[200:201], v[114:117], off
	v_cvt_pk_bf16_f32 v118, v118, v119
	v_cvt_pk_bf16_f32 v119, v120, v121
	v_cvt_pk_bf16_f32 v120, v192, v193
	v_cvt_pk_bf16_f32 v121, v194, v195
	global_store_dwordx4 v[200:201], v[118:121], off offset:256
	s_waitcnt lgkmcnt(0)
	v_add_f32_e32 v115, v126, v127
	v_lshlrev_b32_e32 v114, 2, v191
	ds_bpermute_b32 v116, v114, v115
	s_and_saveexec_b64 s[2:3], s[4:5]
	s_cbranch_execz .LBB0_1846
	s_waitcnt lgkmcnt(0)
	v_add_f32_e32 v115, v115, v116
	ds_write_b32 v184, v115
